# pcmp K-loop: touch the A chunk three K chunks ahead (younger than the W1 loads, left outstanding by the counted waits) so the one-ahead request finds it in L2
# baseline (speedup 1.0000x reference)
; #define LAS __attribute__((address_space(3)))
; DI void pcmp_unit(const Args& a, LAS unsigned char* lds, int kind, int seq, int quarter, int wave, int lane) {
;     ...
;     u32x4 areg[2];
; #pragma unroll
;     for (int i = 0; i < 2; ++i) { const int idx = tid + 512 * i, rw = idx >> 5, ch = idx & 31; areg[i] = *(const u32x4*)(Ab + (size_t)rw * 1024 + ch * 8); }
;     __syncthreads();
; #pragma unroll 1
;     for (int kc = 0; kc < 8; ++kc) {
;         LAS unsigned char* abuf = lds + 65536 + (kc & 1) * 32768;
; #pragma unroll
;         for (int i = 0; i < 2; ++i) { const int idx = tid + 512 * i, rw = idx >> 5, ch = idx & 31; *(LAS u32x4*)(abuf + paoff(rw, ch)) = areg[i]; }
;         __syncthreads();
;         if (kc + 1 < 8) {
; #pragma unroll
;             for (int i = 0; i < 2; ++i) { const int idx = tid + 512 * i, rw = idx >> 5, ch = idx & 31; areg[i] = *(const u32x4*)(Ab + (size_t)rw * 1024 + (kc + 1) * 256 + ch * 8); } }
;         bf16x8 bfr[8][2];
; #pragma unroll
;         for (int ks = 0; ks < 8; ++ks)
; #pragma unroll
;             for (int nt = 0; nt < 2; ++nt) bfr[ks][nt] = *(const bf16x8*)(B + (size_t)nt * 16 * 2048 + kc * 256 + 32 * ks);
; #pragma unroll
;         for (int ks = 0; ks < 8; ++ks)
; #pragma unroll
;             for (int mt = 0; mt < 2; ++mt) { const bf16x8 af = *(const LAS bf16x8*)(abuf + paoff(16 * mt + fr, 4 * ks + fq));
; #pragma unroll
;                 for (int nt = 0; nt < 2; ++nt) acc[mt][nt] = __builtin_amdgcn_mfma_f32_16x16x32_bf16(af, bfr[ks][nt], acc[mt][nt], 0, 0, 0); }
;     }
.LBB0_1301:
	s_sub_i32 s2, s38, 32
	s_ashr_i32 s3, s2, 31
	s_lshr_b32 s3, s3, 25
	s_add_i32 s3, s2, s3
	s_and_b32 s3, s3, 0xffffff80
	s_sub_i32 s3, s2, s3
	s_ashr_i32 s2, s3, 6
	s_lshl_b32 s3, s3, 5
	s_and_b32 s6, s3, 0x7e0
	s_ashr_i32 s3, s2, 31
	s_mul_i32 s12, s2, 0x8402000
	s_mul_hi_i32 s7, s2, 0x8402000
	s_add_u32 s4, s8, s12
	s_addc_u32 s5, s9, s7
	s_lshl_b32 s13, s6, 11
	s_add_u32 s4, s4, s13
	s_addc_u32 s5, s5, 0
	v_lshl_add_u64 v[2:3], s[4:5], 0, v[26:27]
	v_lshl_add_u64 v[4:5], v[2:3], 0, v[30:31]
	v_lshl_add_u64 v[2:3], v[2:3], 0, v[32:33]
	global_load_dwordx4 v[10:13], v[4:5], off
	global_load_dwordx4 v[14:17], v[2:3], off
	global_load_dword v220, v[4:5], off offset:1024
	global_load_dword v220, v[2:3], off offset:1024
	s_lshl_b64 s[4:5], s[2:3], 20
	v_lshl_add_u64 v[46:47], v[40:41], 0, s[4:5]
	s_add_u32 s4, s12, s13
	s_addc_u32 s5, s7, 0
	v_mov_b32_e32 v22, 0
	v_lshl_add_u64 v[48:49], v[42:43], 0, s[4:5]
	v_lshl_add_u64 v[50:51], v[44:45], 0, s[4:5]
	s_mov_b64 s[4:5], 0
	s_mov_b32 s7, 0
	v_mov_b32_e32 v23, v22
	v_mov_b32_e32 v24, v22
	v_mov_b32_e32 v25, v22
	v_mov_b32_e32 v18, v22
	v_mov_b32_e32 v19, v22
	v_mov_b32_e32 v20, v22
	v_mov_b32_e32 v21, v22
	v_mov_b32_e32 v6, v22
	v_mov_b32_e32 v7, v22
	v_mov_b32_e32 v8, v22
	v_mov_b32_e32 v9, v22
	v_mov_b32_e32 v2, v22
	v_mov_b32_e32 v3, v22
	v_mov_b32_e32 v4, v22
	v_mov_b32_e32 v5, v22
	s_waitcnt vmcnt(63) expcnt(7) lgkmcnt(15)
	s_barrier
	s_branch .LBB0_1303
.LBB0_1302:
	v_lshl_add_u64 v[88:89], v[46:47], 0, s[4:5]
	v_add_co_u32_e32 v96, vcc, 0x2080000, v88
	v_add_u32_e32 v100, s12, v28
	s_nop 0
	v_addc_co_u32_e32 v97, vcc, 0, v89, vcc
	v_add_co_u32_e32 v98, vcc, 0x2090000, v88
	s_nop 1
	v_addc_co_u32_e32 v99, vcc, 0, v89, vcc
	global_load_dwordx4 v[132:135], v[96:97], off
	global_load_dwordx4 v[136:139], v[98:99], off
	global_load_dwordx4 v[140:143], v[96:97], off offset:64
	global_load_dwordx4 v[144:147], v[98:99], off offset:64
	global_load_dwordx4 v[148:151], v[96:97], off offset:128
	global_load_dwordx4 v[152:155], v[98:99], off offset:128
	global_load_dwordx4 v[160:163], v[96:97], off offset:192
	global_load_dwordx4 v[168:171], v[98:99], off offset:192
	global_load_dwordx4 v[172:175], v[96:97], off offset:256
	global_load_dwordx4 v[176:179], v[98:99], off offset:256
	global_load_dwordx4 v[180:183], v[96:97], off offset:320
	global_load_dwordx4 v[188:191], v[98:99], off offset:320
	global_load_dwordx4 v[192:195], v[96:97], off offset:384
	global_load_dwordx4 v[196:199], v[98:99], off offset:384
	global_load_dwordx4 v[200:203], v[96:97], off offset:448
	global_load_dwordx4 v[204:207], v[98:99], off offset:448
	v_lshl_add_u64 v[216:217], v[50:51], 0, s[4:5]
	global_load_dword v220, v[216:217], off offset:1024
	v_lshl_add_u64 v[216:217], v[48:49], 0, s[4:5]
	global_load_dword v220, v[216:217], off offset:1024
	v_add_u32_e32 v101, v100, v52
	ds_read_b128 v[76:79], v101
	ds_read_b128 v[84:87], v101 offset:8192
	s_add_u32 s4, s4, 0x200
	s_addc_u32 s5, s5, 0
	s_add_i32 s7, s7, 0x8000
	s_cmpk_lg_i32 s4, 0x1000
	v_add_u32_e32 v101, v100, v53
	ds_read_b128 v[80:83], v101
	ds_read_b128 v[88:91], v101 offset:8192
	s_waitcnt vmcnt(16) lgkmcnt(2)
	v_mfma_f32_16x16x32_bf16 v[22:25], v[76:79], v[132:135], v[22:25]
	v_mfma_f32_16x16x32_bf16 v[6:9], v[84:87], v[132:135], v[6:9]
	v_mfma_f32_16x16x32_bf16 v[18:21], v[76:79], v[136:139], v[18:21]
	v_mfma_f32_16x16x32_bf16 v[2:5], v[84:87], v[136:139], v[2:5]
	v_add_u32_e32 v101, v100, v54
	ds_read_b128 v[76:79], v101
	ds_read_b128 v[84:87], v101 offset:8192
	s_waitcnt vmcnt(14) lgkmcnt(2)
	v_mfma_f32_16x16x32_bf16 v[22:25], v[80:83], v[140:143], v[22:25]
	v_mfma_f32_16x16x32_bf16 v[6:9], v[88:91], v[140:143], v[6:9]
	v_mfma_f32_16x16x32_bf16 v[18:21], v[80:83], v[144:147], v[18:21]
	v_mfma_f32_16x16x32_bf16 v[2:5], v[88:91], v[144:147], v[2:5]
	v_add_u32_e32 v101, v100, v55
	ds_read_b128 v[80:83], v101
	ds_read_b128 v[88:91], v101 offset:8192
	s_waitcnt vmcnt(12) lgkmcnt(2)
	v_mfma_f32_16x16x32_bf16 v[22:25], v[76:79], v[148:151], v[22:25]
	v_mfma_f32_16x16x32_bf16 v[6:9], v[84:87], v[148:151], v[6:9]
	v_mfma_f32_16x16x32_bf16 v[18:21], v[76:79], v[152:155], v[18:21]
	v_mfma_f32_16x16x32_bf16 v[2:5], v[84:87], v[152:155], v[2:5]
	v_add_u32_e32 v101, v100, v66
	ds_read_b128 v[76:79], v101
	ds_read_b128 v[84:87], v101 offset:8192
	s_waitcnt vmcnt(10) lgkmcnt(2)
	v_mfma_f32_16x16x32_bf16 v[22:25], v[80:83], v[160:163], v[22:25]
	v_mfma_f32_16x16x32_bf16 v[6:9], v[88:91], v[160:163], v[6:9]
	v_mfma_f32_16x16x32_bf16 v[18:21], v[80:83], v[168:171], v[18:21]
	v_mfma_f32_16x16x32_bf16 v[2:5], v[88:91], v[168:171], v[2:5]
	v_add_u32_e32 v101, v100, v67
	ds_read_b128 v[80:83], v101
	ds_read_b128 v[88:91], v101 offset:8192
	s_waitcnt vmcnt(8) lgkmcnt(2)
	v_mfma_f32_16x16x32_bf16 v[22:25], v[76:79], v[172:175], v[22:25]
	v_mfma_f32_16x16x32_bf16 v[6:9], v[84:87], v[172:175], v[6:9]
	v_mfma_f32_16x16x32_bf16 v[18:21], v[76:79], v[176:179], v[18:21]
	v_mfma_f32_16x16x32_bf16 v[2:5], v[84:87], v[176:179], v[2:5]
	v_add_u32_e32 v101, v100, v68
	ds_read_b128 v[76:79], v101
	ds_read_b128 v[84:87], v101 offset:8192
	s_waitcnt vmcnt(6) lgkmcnt(2)
	v_mfma_f32_16x16x32_bf16 v[22:25], v[80:83], v[180:183], v[22:25]
	v_mfma_f32_16x16x32_bf16 v[6:9], v[88:91], v[180:183], v[6:9]
	v_mfma_f32_16x16x32_bf16 v[18:21], v[80:83], v[188:191], v[18:21]
	v_mfma_f32_16x16x32_bf16 v[2:5], v[88:91], v[188:191], v[2:5]
	v_add_u32_e32 v101, v100, v69
	ds_read_b128 v[80:83], v101
	ds_read_b128 v[88:91], v101 offset:8192
	s_waitcnt vmcnt(4) lgkmcnt(2)
	v_mfma_f32_16x16x32_bf16 v[22:25], v[76:79], v[192:195], v[22:25]
	v_mfma_f32_16x16x32_bf16 v[6:9], v[84:87], v[192:195], v[6:9]
	v_mfma_f32_16x16x32_bf16 v[18:21], v[76:79], v[196:199], v[18:21]
	v_mfma_f32_16x16x32_bf16 v[2:5], v[84:87], v[196:199], v[2:5]
	s_waitcnt vmcnt(2) lgkmcnt(0)
	v_mfma_f32_16x16x32_bf16 v[22:25], v[80:83], v[200:203], v[22:25]
	v_mfma_f32_16x16x32_bf16 v[6:9], v[88:91], v[200:203], v[6:9]
	v_mfma_f32_16x16x32_bf16 v[18:21], v[80:83], v[204:207], v[18:21]
	v_mfma_f32_16x16x32_bf16 v[2:5], v[88:91], v[204:207], v[2:5]
	s_cbranch_scc0 .LBB0_1305
.LBB0_1303:
	s_and_b32 s12, s7, 0x8000
	s_add_i32 s12, s12, 0
	s_add_i32 s12, s12, 0x10000
	v_add3_u32 v76, s12, v70, v29
	s_waitcnt vmcnt(3)
	ds_write_b128 v76, v[10:13]
	v_add3_u32 v76, s12, v72, v71
	s_cmpk_eq_i32 s4, 0xe00
	s_waitcnt vmcnt(2)
	ds_write_b128 v76, v[14:17]
	s_waitcnt lgkmcnt(0)
	s_barrier
	s_cbranch_scc1 .LBB0_1302
	v_lshl_add_u64 v[10:11], v[50:51], 0, s[4:5]
	v_lshl_add_u64 v[14:15], v[48:49], 0, s[4:5]
	global_load_dwordx4 v[10:13], v[10:11], off
	s_nop 0
	global_load_dwordx4 v[14:17], v[14:15], off
	s_branch .LBB0_1302
